# GEMM K-loops: As[0][0] stage of K-tile t+2 moved from SP2(t) (6 loads) to SP1(t+1) (2->4 loads), SP2(t) wait vmcnt(6)
# speedup vs baseline: 1.0102x; 1.0102x over previous
; #define PG8_STAGE(bufoff, gbase, voff) do { _Pragma("unroll") for (int _i = 0; _i < 2; ++_i) \
;         __builtin_amdgcn_global_load_lds((const unsigned*)((const char*)(gbase) + (voff)[_i]), (PG8_LAS unsigned*)(lds + (bufoff) + ldsw + _i * 8192), 16, 0, 0); } while (0)
; #define PG8_LDA(dst, b, h) do { _Pragma("unroll") for (int m = 0; m < 4; ++m) _Pragma("unroll") for (int k = 0; k < 2; ++k) dst[m][k] = *(const PG8_LAS bf16x8*)(lds + PG8_SA(b, h) + aoff + m * 2048 + k * 1024); } while (0)
; #define PG8_LDB(dst, b, h) do { _Pragma("unroll") for (int n = 0; n < 2; ++n) _Pragma("unroll") for (int k = 0; k < 2; ++k) dst[n][k] = *(const PG8_LAS bf16x8*)(lds + PG8_SB(b, h) + boff + n * 2048 + k * 1024); } while (0)
; #define PG8_MMA(ai, bj, At, Bt) do { __builtin_amdgcn_s_setprio(1); _Pragma("unroll") for (int m = 0; m < 4; ++m) _Pragma("unroll") for (int n = 0; n < 2; ++n) _Pragma("unroll") for (int k = 0; k < 2; ++k) \
;         acc[ai][bj][m][n] = __builtin_amdgcn_mfma_f32_16x16x32_bf16(Bt[n][k], At[m][k], acc[ai][bj][m][n], 0, 0, 0); __builtin_amdgcn_s_setprio(0); } while (0)
; #define PG8_WAIT_V(n) asm volatile("s_waitcnt vmcnt(" #n ")" ::: "memory")
; #define PG8_BAR __builtin_amdgcn_s_barrier()
; template <class Epi, class Sched, bool ALIGN_EPI = false, bool SP2 = false>
; __device__ __forceinline__ void gemm_phase(PG8_LAS unsigned char* lds, const Gemm g, const Sched& S, const Epi& E) {
;     ...
;         for (int t = 0; t < nt; t += 2) {
;             const bool last = (t == nt - 2);
;             const char* a1 = cA + (size_t)(t + 1) * kstep;
;             const char* a2 = last ? nA : cA + (size_t)(t + 2) * kstep; const char* b2 = last ? nB : cB + (size_t)(t + 2) * kstep;
;             const char* a3 = a2 + kstep; const char* b3 = b2 + kstep;
;             if (last && has_next) S.a_ready(nxt);
;             if constexpr (SP2) {
;             PG8_LDB(B0, 0, 0); PG8_LDB(B1, 0, 1); PG8_SCHED; PG8_LDA(At, 0, 0); PG8_STAGE(PG8_SA(1, 1), a1 + hstep, voffA);
;             PG8_WAIT_V(8); PG8_WAIT_L(0); PG8_BAR; PG8_MMA(0, 0, At, B0); PG8_MMA(0, 1, At, B1); PG8_BAR; PG8_SCHED;
;             PG8_LDA(At, 0, 1); PG8_STAGE(PG8_SB(0, 0), b2, voffB); PG8_STAGE(PG8_SB(0, 1), b2 + hstep, voffB); PG8_STAGE(PG8_SA(0, 0), a2, voffA);
;             PG8_WAIT_V(8); PG8_WAIT_L(0); PG8_BAR; PG8_MMA(1, 0, At, B0); PG8_MMA(1, 1, At, B1); PG8_BAR; PG8_SCHED;
.LBB0_230:
	s_add_u32 s35, s62, 0xfffc0080
	s_addc_u32 s64, s63, -1
	s_add_i32 s68, 0, 0x10000
	s_cmp_eq_u32 s33, 12
	s_cselect_b32 s67, s1, s64
	s_cselect_b32 s66, s14, s35
	v_add_u32_e32 v0, s68, v185
	s_cselect_b32 s65, s15, s29
	s_cselect_b32 s64, s20, s28
	s_add_i32 s35, 0, 0x14000
	ds_read_b128 v[130:133], v0
	ds_read_b128 v[134:137], v0 offset:1024
	ds_read_b128 v[138:141], v0 offset:2048
	ds_read_b128 v[142:145], v0 offset:3072
	v_add_u32_e32 v0, s35, v185
	ds_read_b128 v[146:149], v0
	ds_read_b128 v[150:153], v0 offset:1024
	ds_read_b128 v[154:157], v0 offset:2048
	ds_read_b128 v[158:161], v0 offset:3072
	v_lshl_add_u64 v[236:237], s[62:63], 0, v[208:209]
	s_add_i32 m0, s82, 0xc000
	ds_read_b128 v[162:165], v187
	ds_read_b128 v[166:169], v187 offset:1024
	ds_read_b128 v[170:173], v187 offset:2048
	ds_read_b128 v[174:177], v187 offset:3072
	ds_read_b128 v[210:213], v187 offset:4096
	ds_read_b128 v[214:217], v187 offset:5120
	ds_read_b128 v[228:231], v187 offset:6144
	ds_read_b128 v[232:235], v187 offset:7168
	global_load_lds_dwordx4 v[236:237], off
	v_lshl_add_u64 v[236:237], s[62:63], 0, v[206:207]
	s_add_i32 m0, s82, 0xe000
	s_nop 0
	global_load_lds_dwordx4 v[236:237], off
	s_waitcnt vmcnt(8)
	s_waitcnt lgkmcnt(0)
	s_barrier
	s_setprio 1
	s_waitcnt lgkmcnt(0)
	v_mfma_f32_16x16x32_bf16 v[126:129], v[130:133], v[162:165], v[126:129]
	v_mfma_f32_16x16x32_bf16 v[122:125], v[138:141], v[162:165], v[122:125]
	v_mfma_f32_16x16x32_bf16 v[94:97], v[130:133], v[170:173], v[94:97]
	v_mfma_f32_16x16x32_bf16 v[90:93], v[138:141], v[170:173], v[90:93]
	v_mfma_f32_16x16x32_bf16 v[62:65], v[130:133], v[210:213], v[62:65]
	v_mfma_f32_16x16x32_bf16 v[58:61], v[138:141], v[210:213], v[58:61]
	v_mfma_f32_16x16x32_bf16 v[30:33], v[130:133], v[228:231], v[30:33]
	v_mfma_f32_16x16x32_bf16 v[26:29], v[138:141], v[228:231], v[26:29]
	v_mfma_f32_16x16x32_bf16 v[126:129], v[134:137], v[166:169], v[126:129]
	v_mfma_f32_16x16x32_bf16 v[122:125], v[142:145], v[166:169], v[122:125]
	v_mfma_f32_16x16x32_bf16 v[94:97], v[134:137], v[174:177], v[94:97]
	v_mfma_f32_16x16x32_bf16 v[90:93], v[142:145], v[174:177], v[90:93]
	v_mfma_f32_16x16x32_bf16 v[62:65], v[134:137], v[214:217], v[62:65]
	v_mfma_f32_16x16x32_bf16 v[58:61], v[142:145], v[214:217], v[58:61]
	v_mfma_f32_16x16x32_bf16 v[30:33], v[134:137], v[232:235], v[30:33]
	v_mfma_f32_16x16x32_bf16 v[26:29], v[142:145], v[232:235], v[26:29]
	s_setprio 0
	s_setprio 1
	v_mfma_f32_16x16x32_bf16 v[118:121], v[146:149], v[162:165], v[118:121]
	v_mfma_f32_16x16x32_bf16 v[114:117], v[154:157], v[162:165], v[114:117]
	v_mfma_f32_16x16x32_bf16 v[86:89], v[146:149], v[170:173], v[86:89]
	v_mfma_f32_16x16x32_bf16 v[82:85], v[154:157], v[170:173], v[82:85]
	v_mfma_f32_16x16x32_bf16 v[54:57], v[146:149], v[210:213], v[54:57]
	v_mfma_f32_16x16x32_bf16 v[50:53], v[154:157], v[210:213], v[50:53]
	v_mfma_f32_16x16x32_bf16 v[22:25], v[146:149], v[228:231], v[22:25]
	v_mfma_f32_16x16x32_bf16 v[18:21], v[154:157], v[228:231], v[18:21]
	v_mfma_f32_16x16x32_bf16 v[118:121], v[150:153], v[166:169], v[118:121]
	v_mfma_f32_16x16x32_bf16 v[114:117], v[158:161], v[166:169], v[114:117]
	v_mfma_f32_16x16x32_bf16 v[86:89], v[150:153], v[174:177], v[86:89]
	v_mfma_f32_16x16x32_bf16 v[82:85], v[158:161], v[174:177], v[82:85]
	v_mfma_f32_16x16x32_bf16 v[54:57], v[150:153], v[214:217], v[54:57]
	v_mfma_f32_16x16x32_bf16 v[50:53], v[158:161], v[214:217], v[50:53]
	v_mfma_f32_16x16x32_bf16 v[22:25], v[150:153], v[232:235], v[22:25]
	v_mfma_f32_16x16x32_bf16 v[18:21], v[158:161], v[232:235], v[18:21]
	s_setprio 0
	s_barrier
	s_add_i32 s68, s68, s81
	v_lshl_add_u64 v[236:237], s[64:65], 0, v[180:181]
	s_mov_b32 m0, s68
	ds_read_b128 v[162:165], v187 offset:16384
	ds_read_b128 v[166:169], v187 offset:17408
	ds_read_b128 v[170:173], v187 offset:18432
	ds_read_b128 v[174:177], v187 offset:19456
	ds_read_b128 v[210:213], v187 offset:20480
	ds_read_b128 v[214:217], v187 offset:21504
	ds_read_b128 v[228:231], v187 offset:22528
	ds_read_b128 v[232:235], v187 offset:23552
	global_load_lds_dwordx4 v[236:237], off
	s_add_i32 m0, s68, 0x2000
	s_add_u32 s68, s64, 0x40000
	v_lshl_add_u64 v[238:239], s[64:65], 0, v[178:179]
	s_addc_u32 s69, s65, 0
	s_add_i32 s35, s35, s81
	global_load_lds_dwordx4 v[238:239], off
	v_lshl_add_u64 v[240:241], s[68:69], 0, v[180:181]
	s_mov_b32 m0, s35
	global_load_lds_dwordx4 v[240:241], off
	v_lshl_add_u64 v[240:241], s[68:69], 0, v[178:179]
	s_add_i32 m0, s35, 0x2000
	s_nop 0
	global_load_lds_dwordx4 v[240:241], off
	s_waitcnt vmcnt(6)
	s_waitcnt lgkmcnt(0)
	s_barrier
; #define PG8_STAGE(bufoff, gbase, voff) do { _Pragma("unroll") for (int _i = 0; _i < 2; ++_i) \
;         __builtin_amdgcn_global_load_lds((const unsigned*)((const char*)(gbase) + (voff)[_i]), (PG8_LAS unsigned*)(lds + (bufoff) + ldsw + _i * 8192), 16, 0, 0); } while (0)
; #define PG8_LDA(dst, b, h) do { _Pragma("unroll") for (int m = 0; m < 4; ++m) _Pragma("unroll") for (int k = 0; k < 2; ++k) dst[m][k] = *(const PG8_LAS bf16x8*)(lds + PG8_SA(b, h) + aoff + m * 2048 + k * 1024); } while (0)
; #define PG8_LDB(dst, b, h) do { _Pragma("unroll") for (int n = 0; n < 2; ++n) _Pragma("unroll") for (int k = 0; k < 2; ++k) dst[n][k] = *(const PG8_LAS bf16x8*)(lds + PG8_SB(b, h) + boff + n * 2048 + k * 1024); } while (0)
; #define PG8_MMA(ai, bj, At, Bt) do { __builtin_amdgcn_s_setprio(1); _Pragma("unroll") for (int m = 0; m < 4; ++m) _Pragma("unroll") for (int n = 0; n < 2; ++n) _Pragma("unroll") for (int k = 0; k < 2; ++k) \
;         acc[ai][bj][m][n] = __builtin_amdgcn_mfma_f32_16x16x32_bf16(Bt[n][k], At[m][k], acc[ai][bj][m][n], 0, 0, 0); __builtin_amdgcn_s_setprio(0); } while (0)
; #define PG8_WAIT_V(n) asm volatile("s_waitcnt vmcnt(" #n ")" ::: "memory")
; #define PG8_WAIT_L(n) asm volatile("s_waitcnt lgkmcnt(" #n ")" ::: "memory")
; #define PG8_BAR __builtin_amdgcn_s_barrier()
; #define PG8_SCHED __builtin_amdgcn_sched_barrier(0)
; template <class Epi, class Sched, bool ALIGN_EPI = false, bool SP2 = false>
; __device__ __forceinline__ void gemm_phase(PG8_LAS unsigned char* lds, const Gemm g, const Sched& S, const Epi& E) {
;     ...
;             PG8_WAIT_V(8); PG8_WAIT_L(0); PG8_BAR; PG8_MMA(1, 0, At, B0); PG8_MMA(1, 1, At, B1); PG8_BAR; PG8_SCHED;
;             PG8_LDB(B0, 1, 0); PG8_LDB(B1, 1, 1); PG8_SCHED; PG8_LDA(At, 1, 0); PG8_STAGE(PG8_SA(0, 1), a2 + hstep, voffA);
;             PG8_WAIT_V(8); PG8_WAIT_L(0); PG8_BAR; PG8_MMA(0, 0, At, B0); PG8_MMA(0, 1, At, B1); PG8_BAR; PG8_SCHED;
	s_setprio 1
	s_waitcnt lgkmcnt(0)
	v_mfma_f32_16x16x32_bf16 v[110:113], v[130:133], v[162:165], v[110:113]
	v_mfma_f32_16x16x32_bf16 v[106:109], v[138:141], v[162:165], v[106:109]
	v_mfma_f32_16x16x32_bf16 v[78:81], v[130:133], v[170:173], v[78:81]
	v_mfma_f32_16x16x32_bf16 v[74:77], v[138:141], v[170:173], v[74:77]
	v_mfma_f32_16x16x32_bf16 v[46:49], v[130:133], v[210:213], v[46:49]
	v_mfma_f32_16x16x32_bf16 v[42:45], v[138:141], v[210:213], v[42:45]
	v_mfma_f32_16x16x32_bf16 v[14:17], v[130:133], v[228:231], v[14:17]
	v_mfma_f32_16x16x32_bf16 v[10:13], v[138:141], v[228:231], v[10:13]
	v_mfma_f32_16x16x32_bf16 v[110:113], v[134:137], v[166:169], v[110:113]
	v_mfma_f32_16x16x32_bf16 v[106:109], v[142:145], v[166:169], v[106:109]
	v_mfma_f32_16x16x32_bf16 v[78:81], v[134:137], v[174:177], v[78:81]
	v_mfma_f32_16x16x32_bf16 v[74:77], v[142:145], v[174:177], v[74:77]
	v_mfma_f32_16x16x32_bf16 v[46:49], v[134:137], v[214:217], v[46:49]
	v_mfma_f32_16x16x32_bf16 v[42:45], v[142:145], v[214:217], v[42:45]
	v_mfma_f32_16x16x32_bf16 v[14:17], v[134:137], v[232:235], v[14:17]
	v_mfma_f32_16x16x32_bf16 v[10:13], v[142:145], v[232:235], v[10:13]
	s_setprio 0
	s_setprio 1
	v_mfma_f32_16x16x32_bf16 v[102:105], v[146:149], v[162:165], v[102:105]
	v_mfma_f32_16x16x32_bf16 v[98:101], v[154:157], v[162:165], v[98:101]
	v_mfma_f32_16x16x32_bf16 v[70:73], v[146:149], v[170:173], v[70:73]
	v_mfma_f32_16x16x32_bf16 v[66:69], v[154:157], v[170:173], v[66:69]
	v_mfma_f32_16x16x32_bf16 v[38:41], v[146:149], v[210:213], v[38:41]
	v_mfma_f32_16x16x32_bf16 v[34:37], v[154:157], v[210:213], v[34:37]
	v_mfma_f32_16x16x32_bf16 v[6:9], v[146:149], v[228:231], v[6:9]
	v_mfma_f32_16x16x32_bf16 v[2:5], v[154:157], v[228:231], v[2:5]
	v_mfma_f32_16x16x32_bf16 v[102:105], v[150:153], v[166:169], v[102:105]
	v_mfma_f32_16x16x32_bf16 v[98:101], v[158:161], v[166:169], v[98:101]
	v_mfma_f32_16x16x32_bf16 v[70:73], v[150:153], v[174:177], v[70:73]
	v_mfma_f32_16x16x32_bf16 v[66:69], v[158:161], v[174:177], v[66:69]
	v_mfma_f32_16x16x32_bf16 v[38:41], v[150:153], v[214:217], v[38:41]
	v_mfma_f32_16x16x32_bf16 v[34:37], v[158:161], v[214:217], v[34:37]
	v_mfma_f32_16x16x32_bf16 v[6:9], v[150:153], v[232:235], v[6:9]
	v_mfma_f32_16x16x32_bf16 v[2:5], v[158:161], v[232:235], v[2:5]
	s_setprio 0
	s_barrier
	v_lshl_add_u64 v[240:241], s[66:67], 0, v[180:181]
	s_mov_b32 m0, s82
	v_lshl_add_u64 v[242:243], s[66:67], 0, v[178:179]
	global_load_lds_dwordx4 v[240:241], off
	s_mov_b32 m0, s83
	s_nop 0
	global_load_lds_dwordx4 v[242:243], off
	s_add_i32 s35, 0, 0x18000
	v_add_u32_e32 v0, s35, v185
	s_add_i32 s68, 0, 0x1c000
	ds_read_b128 v[130:133], v0
	ds_read_b128 v[134:137], v0 offset:1024
	ds_read_b128 v[138:141], v0 offset:2048
	ds_read_b128 v[142:145], v0 offset:3072
	v_add_u32_e32 v0, s68, v185
	ds_read_b128 v[146:149], v0
	ds_read_b128 v[150:153], v0 offset:1024
	ds_read_b128 v[154:157], v0 offset:2048
	ds_read_b128 v[158:161], v0 offset:3072
	s_add_u32 s66, s66, 0x40000
	s_addc_u32 s67, s67, 0
	s_mov_b32 m0, s84
	v_lshl_add_u64 v[244:245], s[66:67], 0, v[180:181]
	ds_read_b128 v[162:165], v187 offset:32768
	ds_read_b128 v[166:169], v187 offset:33792
	ds_read_b128 v[170:173], v187 offset:34816
	ds_read_b128 v[174:177], v187 offset:35840
	ds_read_b128 v[210:213], v187 offset:36864
	ds_read_b128 v[214:217], v187 offset:37888
	ds_read_b128 v[228:231], v187 offset:38912
	ds_read_b128 v[232:235], v187 offset:39936
	global_load_lds_dwordx4 v[244:245], off
	v_lshl_add_u64 v[244:245], s[66:67], 0, v[178:179]
	s_mov_b32 m0, s85
	s_nop 0
	global_load_lds_dwordx4 v[244:245], off
	s_waitcnt vmcnt(8)
	s_waitcnt lgkmcnt(0)
	s_barrier
	s_setprio 1
	s_waitcnt lgkmcnt(0)
	v_mfma_f32_16x16x32_bf16 v[126:129], v[130:133], v[162:165], v[126:129]
	v_mfma_f32_16x16x32_bf16 v[122:125], v[138:141], v[162:165], v[122:125]
	v_mfma_f32_16x16x32_bf16 v[94:97], v[130:133], v[170:173], v[94:97]
	v_mfma_f32_16x16x32_bf16 v[90:93], v[138:141], v[170:173], v[90:93]
	v_mfma_f32_16x16x32_bf16 v[62:65], v[130:133], v[210:213], v[62:65]
	v_mfma_f32_16x16x32_bf16 v[58:61], v[138:141], v[210:213], v[58:61]
	v_mfma_f32_16x16x32_bf16 v[30:33], v[130:133], v[228:231], v[30:33]
	v_mfma_f32_16x16x32_bf16 v[26:29], v[138:141], v[228:231], v[26:29]
	v_mfma_f32_16x16x32_bf16 v[126:129], v[134:137], v[166:169], v[126:129]
	v_mfma_f32_16x16x32_bf16 v[122:125], v[142:145], v[166:169], v[122:125]
	v_mfma_f32_16x16x32_bf16 v[94:97], v[134:137], v[174:177], v[94:97]
	v_mfma_f32_16x16x32_bf16 v[90:93], v[142:145], v[174:177], v[90:93]
	v_mfma_f32_16x16x32_bf16 v[62:65], v[134:137], v[214:217], v[62:65]
	v_mfma_f32_16x16x32_bf16 v[58:61], v[142:145], v[214:217], v[58:61]
	v_mfma_f32_16x16x32_bf16 v[30:33], v[134:137], v[232:235], v[30:33]
	v_mfma_f32_16x16x32_bf16 v[26:29], v[142:145], v[232:235], v[26:29]
	s_setprio 0
	s_setprio 1
	v_mfma_f32_16x16x32_bf16 v[118:121], v[146:149], v[162:165], v[118:121]
	v_mfma_f32_16x16x32_bf16 v[114:117], v[154:157], v[162:165], v[114:117]
	v_mfma_f32_16x16x32_bf16 v[86:89], v[146:149], v[170:173], v[86:89]
	v_mfma_f32_16x16x32_bf16 v[82:85], v[154:157], v[170:173], v[82:85]
	v_mfma_f32_16x16x32_bf16 v[54:57], v[146:149], v[210:213], v[54:57]
	v_mfma_f32_16x16x32_bf16 v[50:53], v[154:157], v[210:213], v[50:53]
	v_mfma_f32_16x16x32_bf16 v[22:25], v[146:149], v[228:231], v[22:25]
	v_mfma_f32_16x16x32_bf16 v[18:21], v[154:157], v[228:231], v[18:21]
	v_mfma_f32_16x16x32_bf16 v[118:121], v[150:153], v[166:169], v[118:121]
	v_mfma_f32_16x16x32_bf16 v[114:117], v[158:161], v[166:169], v[114:117]
	v_mfma_f32_16x16x32_bf16 v[86:89], v[150:153], v[174:177], v[86:89]
	v_mfma_f32_16x16x32_bf16 v[82:85], v[158:161], v[174:177], v[82:85]
	v_mfma_f32_16x16x32_bf16 v[54:57], v[150:153], v[214:217], v[54:57]
	v_mfma_f32_16x16x32_bf16 v[50:53], v[158:161], v[214:217], v[50:53]
	v_mfma_f32_16x16x32_bf16 v[22:25], v[150:153], v[232:235], v[22:25]
	v_mfma_f32_16x16x32_bf16 v[18:21], v[158:161], v[232:235], v[18:21]
	s_setprio 0
	s_barrier
; #define PG8_STAGE(bufoff, gbase, voff) do { _Pragma("unroll") for (int _i = 0; _i < 2; ++_i) \
;         __builtin_amdgcn_global_load_lds((const unsigned*)((const char*)(gbase) + (voff)[_i]), (PG8_LAS unsigned*)(lds + (bufoff) + ldsw + _i * 8192), 16, 0, 0); } while (0)
; #define PG8_LDA(dst, b, h) do { _Pragma("unroll") for (int m = 0; m < 4; ++m) _Pragma("unroll") for (int k = 0; k < 2; ++k) dst[m][k] = *(const PG8_LAS bf16x8*)(lds + PG8_SA(b, h) + aoff + m * 2048 + k * 1024); } while (0)
; #define PG8_MMA(ai, bj, At, Bt) do { __builtin_amdgcn_s_setprio(1); _Pragma("unroll") for (int m = 0; m < 4; ++m) _Pragma("unroll") for (int n = 0; n < 2; ++n) _Pragma("unroll") for (int k = 0; k < 2; ++k) \
;         acc[ai][bj][m][n] = __builtin_amdgcn_mfma_f32_16x16x32_bf16(Bt[n][k], At[m][k], acc[ai][bj][m][n], 0, 0, 0); __builtin_amdgcn_s_setprio(0); } while (0)
; #define PG8_WAIT_V(n) asm volatile("s_waitcnt vmcnt(" #n ")" ::: "memory")
; #define PG8_WAIT_L(n) asm volatile("s_waitcnt lgkmcnt(" #n ")" ::: "memory")
; #define PG8_BAR __builtin_amdgcn_s_barrier()
; #define PG8_SCHED __builtin_amdgcn_sched_barrier(0)
; template <class Epi, class Sched, bool ALIGN_EPI = false, bool SP2 = false>
; __device__ __forceinline__ void gemm_phase(PG8_LAS unsigned char* lds, const Gemm g, const Sched& S, const Epi& E) {
;     ...
;         for (int t = 0; t < nt; t += 2) {
;     ...
;             PG8_WAIT_V(8); PG8_WAIT_L(0); PG8_BAR; PG8_MMA(0, 0, At, B0); PG8_MMA(0, 1, At, B1); PG8_BAR; PG8_SCHED;
;             PG8_LDA(At, 1, 1); PG8_STAGE(PG8_SB(1, 0), b3, voffB); PG8_STAGE(PG8_SB(1, 1), b3 + hstep, voffB); PG8_STAGE(PG8_SA(1, 0), a3, voffA);
;             PG8_WAIT_V(8); PG8_WAIT_L(0); PG8_BAR; PG8_MMA(1, 0, At, B0); PG8_MMA(1, 1, At, B1); PG8_BAR; PG8_SCHED;
	s_add_i32 s35, s35, s81
	v_lshl_add_u64 v[236:237], v[236:237], 0, s[38:39]
	s_mov_b32 m0, s35
	ds_read_b128 v[162:165], v187 offset:49152
	ds_read_b128 v[166:169], v187 offset:50176
	ds_read_b128 v[170:173], v187 offset:51200
	ds_read_b128 v[174:177], v187 offset:52224
	ds_read_b128 v[210:213], v187 offset:53248
	ds_read_b128 v[214:217], v187 offset:54272
	ds_read_b128 v[228:231], v187 offset:55296
	ds_read_b128 v[232:235], v187 offset:56320
	global_load_lds_dwordx4 v[236:237], off
	s_add_i32 m0, s35, 0x2000
	s_add_u32 s64, s64, 0x40080
	v_lshl_add_u64 v[236:237], v[238:239], 0, s[38:39]
	s_addc_u32 s65, s65, 0
	s_add_i32 s35, s68, s81
	global_load_lds_dwordx4 v[236:237], off
	v_lshl_add_u64 v[236:237], s[64:65], 0, v[180:181]
	s_mov_b32 m0, s35
	s_nop 0
	global_load_lds_dwordx4 v[236:237], off
	v_lshl_add_u64 v[236:237], s[64:65], 0, v[178:179]
	s_add_i32 m0, s35, 0x2000
	s_nop 0
	global_load_lds_dwordx4 v[236:237], off
	v_lshl_add_u64 v[236:237], v[240:241], 0, s[38:39]
	s_mov_b32 m0, s88
	s_nop 0
	global_load_lds_dwordx4 v[236:237], off
	v_lshl_add_u64 v[236:237], v[242:243], 0, s[38:39]
	s_mov_b32 m0, s89
	s_nop 0
	global_load_lds_dwordx4 v[236:237], off
	s_waitcnt vmcnt(8)
	s_waitcnt lgkmcnt(0)
	s_barrier
	s_setprio 1
	s_waitcnt lgkmcnt(0)
	v_mfma_f32_16x16x32_bf16 v[110:113], v[130:133], v[162:165], v[110:113]
	v_mfma_f32_16x16x32_bf16 v[106:109], v[138:141], v[162:165], v[106:109]
	v_mfma_f32_16x16x32_bf16 v[78:81], v[130:133], v[170:173], v[78:81]
	v_mfma_f32_16x16x32_bf16 v[74:77], v[138:141], v[170:173], v[74:77]
	v_mfma_f32_16x16x32_bf16 v[46:49], v[130:133], v[210:213], v[46:49]
	v_mfma_f32_16x16x32_bf16 v[42:45], v[138:141], v[210:213], v[42:45]
	v_mfma_f32_16x16x32_bf16 v[14:17], v[130:133], v[228:231], v[14:17]
	v_mfma_f32_16x16x32_bf16 v[10:13], v[138:141], v[228:231], v[10:13]
	v_mfma_f32_16x16x32_bf16 v[110:113], v[134:137], v[166:169], v[110:113]
	v_mfma_f32_16x16x32_bf16 v[106:109], v[142:145], v[166:169], v[106:109]
	v_mfma_f32_16x16x32_bf16 v[78:81], v[134:137], v[174:177], v[78:81]
	v_mfma_f32_16x16x32_bf16 v[74:77], v[142:145], v[174:177], v[74:77]
	v_mfma_f32_16x16x32_bf16 v[46:49], v[134:137], v[214:217], v[46:49]
	v_mfma_f32_16x16x32_bf16 v[42:45], v[142:145], v[214:217], v[42:45]
	v_mfma_f32_16x16x32_bf16 v[14:17], v[134:137], v[232:235], v[14:17]
	v_mfma_f32_16x16x32_bf16 v[10:13], v[142:145], v[232:235], v[10:13]
	s_setprio 0
	s_setprio 1
	v_mfma_f32_16x16x32_bf16 v[102:105], v[146:149], v[162:165], v[102:105]
	v_mfma_f32_16x16x32_bf16 v[98:101], v[154:157], v[162:165], v[98:101]
	v_mfma_f32_16x16x32_bf16 v[70:73], v[146:149], v[170:173], v[70:73]
	v_mfma_f32_16x16x32_bf16 v[66:69], v[154:157], v[170:173], v[66:69]
	v_mfma_f32_16x16x32_bf16 v[38:41], v[146:149], v[210:213], v[38:41]
	v_mfma_f32_16x16x32_bf16 v[34:37], v[154:157], v[210:213], v[34:37]
	v_mfma_f32_16x16x32_bf16 v[6:9], v[146:149], v[228:231], v[6:9]
	v_mfma_f32_16x16x32_bf16 v[2:5], v[154:157], v[228:231], v[2:5]
	v_mfma_f32_16x16x32_bf16 v[102:105], v[150:153], v[166:169], v[102:105]
	v_mfma_f32_16x16x32_bf16 v[98:101], v[158:161], v[166:169], v[98:101]
	v_mfma_f32_16x16x32_bf16 v[70:73], v[150:153], v[174:177], v[70:73]
	v_mfma_f32_16x16x32_bf16 v[66:69], v[158:161], v[174:177], v[66:69]
	v_mfma_f32_16x16x32_bf16 v[38:41], v[150:153], v[214:217], v[38:41]
	v_mfma_f32_16x16x32_bf16 v[34:37], v[158:161], v[214:217], v[34:37]
	v_mfma_f32_16x16x32_bf16 v[6:9], v[150:153], v[232:235], v[6:9]
	v_mfma_f32_16x16x32_bf16 v[2:5], v[158:161], v[232:235], v[2:5]
	s_setprio 0
	s_barrier
	s_add_i32 s33, s33, 2
	s_add_u32 s28, s28, 0x100
	s_addc_u32 s29, s29, 0
	s_add_u32 s62, s62, 0x100
	s_addc_u32 s63, s63, 0
	s_cmp_gt_u32 s33, 13
	s_cbranch_scc0 .LBB0_230
	s_and_b64 vcc, exec, s[48:49]
	s_cbranch_vccz .LBB0_233
	s_barrier

; #define PG8_STAGE(bufoff, gbase, voff) do { _Pragma("unroll") for (int _i = 0; _i < 2; ++_i) \
;         __builtin_amdgcn_global_load_lds((const unsigned*)((const char*)(gbase) + (voff)[_i]), (PG8_LAS unsigned*)(lds + (bufoff) + ldsw + _i * 8192), 16, 0, 0); } while (0)
; #define PG8_LDA(dst, b, h) do { _Pragma("unroll") for (int m = 0; m < 4; ++m) _Pragma("unroll") for (int k = 0; k < 2; ++k) dst[m][k] = *(const PG8_LAS bf16x8*)(lds + PG8_SA(b, h) + aoff + m * 2048 + k * 1024); } while (0)
; #define PG8_LDB(dst, b, h) do { _Pragma("unroll") for (int n = 0; n < 2; ++n) _Pragma("unroll") for (int k = 0; k < 2; ++k) dst[n][k] = *(const PG8_LAS bf16x8*)(lds + PG8_SB(b, h) + boff + n * 2048 + k * 1024); } while (0)
; #define PG8_MMA(ai, bj, At, Bt) do { __builtin_amdgcn_s_setprio(1); _Pragma("unroll") for (int m = 0; m < 4; ++m) _Pragma("unroll") for (int n = 0; n < 2; ++n) _Pragma("unroll") for (int k = 0; k < 2; ++k) \
;         acc[ai][bj][m][n] = __builtin_amdgcn_mfma_f32_16x16x32_bf16(Bt[n][k], At[m][k], acc[ai][bj][m][n], 0, 0, 0); __builtin_amdgcn_s_setprio(0); } while (0)
; #define PG8_WAIT_V(n) asm volatile("s_waitcnt vmcnt(" #n ")" ::: "memory")
; #define PG8_BAR __builtin_amdgcn_s_barrier()
; template <class Epi, class Sched, bool ALIGN_EPI = false, bool SP2 = false>
; __device__ __forceinline__ void gemm_phase(PG8_LAS unsigned char* lds, const Gemm g, const Sched& S, const Epi& E) {
;     ...
;         for (int t = 0; t < nt; t += 2) {
;             const bool last = (t == nt - 2);
;             const char* a1 = cA + (size_t)(t + 1) * kstep;
;             const char* a2 = last ? nA : cA + (size_t)(t + 2) * kstep; const char* b2 = last ? nB : cB + (size_t)(t + 2) * kstep;
;             const char* a3 = a2 + kstep; const char* b3 = b2 + kstep;
;             if (last && has_next) S.a_ready(nxt);
;             if constexpr (SP2) {
;             PG8_LDB(B0, 0, 0); PG8_LDB(B1, 0, 1); PG8_SCHED; PG8_LDA(At, 0, 0); PG8_STAGE(PG8_SA(1, 1), a1 + hstep, voffA);
;             PG8_WAIT_V(8); PG8_WAIT_L(0); PG8_BAR; PG8_MMA(0, 0, At, B0); PG8_MMA(0, 1, At, B1); PG8_BAR; PG8_SCHED;
;             PG8_LDA(At, 0, 1); PG8_STAGE(PG8_SB(0, 0), b2, voffB); PG8_STAGE(PG8_SB(0, 1), b2 + hstep, voffB); PG8_STAGE(PG8_SA(0, 0), a2, voffA);
;             PG8_WAIT_V(8); PG8_WAIT_L(0); PG8_BAR; PG8_MMA(1, 0, At, B0); PG8_MMA(1, 1, At, B1); PG8_BAR; PG8_SCHED;
.LBB0_678:
	s_add_u32 s60, s42, 0xfffc0080
	s_addc_u32 s61, s43, -1
	s_add_i32 s80, 0, 0x10000
	s_cmp_eq_u32 s79, 12
	s_cselect_b32 s63, s49, s61
	s_cselect_b32 s62, s75, s60
	v_add_u32_e32 v0, s80, v159
	s_cselect_b32 s61, s47, s78
	s_cselect_b32 s60, s76, s77
	s_add_i32 s82, 0, 0x14000
	ds_read_b128 v[102:105], v0
	ds_read_b128 v[110:113], v0 offset:1024
	ds_read_b128 v[114:117], v0 offset:2048
	ds_read_b128 v[118:121], v0 offset:3072
	v_add_u32_e32 v0, s82, v159
	ds_read_b128 v[162:165], v0
	ds_read_b128 v[166:169], v0 offset:1024
	ds_read_b128 v[170:173], v0 offset:2048
	ds_read_b128 v[174:177], v0 offset:3072
	v_lshl_add_u64 v[232:233], s[42:43], 0, v[156:157]
	s_add_i32 m0, s28, 0xc000
	ds_read_b128 v[178:181], v161
	ds_read_b128 v[182:185], v161 offset:1024
	ds_read_b128 v[186:189], v161 offset:2048
	ds_read_b128 v[202:205], v161 offset:3072
	ds_read_b128 v[206:209], v161 offset:4096
	ds_read_b128 v[210:213], v161 offset:5120
	ds_read_b128 v[214:217], v161 offset:6144
	ds_read_b128 v[228:231], v161 offset:7168
	global_load_lds_dwordx4 v[232:233], off
	v_lshl_add_u64 v[232:233], s[42:43], 0, v[154:155]
	s_add_i32 m0, s28, 0xe000
	s_nop 0
	global_load_lds_dwordx4 v[232:233], off
	s_waitcnt vmcnt(8)
	s_waitcnt lgkmcnt(0)
	s_barrier
	s_setprio 1
	s_waitcnt lgkmcnt(0)
	v_mfma_f32_16x16x32_bf16 v[142:145], v[102:105], v[178:181], v[142:145]
	v_mfma_f32_16x16x32_bf16 v[138:141], v[114:117], v[178:181], v[138:141]
	v_mfma_f32_16x16x32_bf16 v[126:129], v[102:105], v[186:189], v[126:129]
	v_mfma_f32_16x16x32_bf16 v[122:125], v[114:117], v[186:189], v[122:125]
	v_mfma_f32_16x16x32_bf16 v[94:97], v[102:105], v[206:209], v[94:97]
	v_mfma_f32_16x16x32_bf16 v[90:93], v[114:117], v[206:209], v[90:93]
	v_mfma_f32_16x16x32_bf16 v[82:85], v[102:105], v[214:217], v[82:85]
	v_mfma_f32_16x16x32_bf16 v[74:77], v[114:117], v[214:217], v[74:77]
	v_mfma_f32_16x16x32_bf16 v[142:145], v[110:113], v[182:185], v[142:145]
	v_mfma_f32_16x16x32_bf16 v[138:141], v[118:121], v[182:185], v[138:141]
	v_mfma_f32_16x16x32_bf16 v[126:129], v[110:113], v[202:205], v[126:129]
	v_mfma_f32_16x16x32_bf16 v[122:125], v[118:121], v[202:205], v[122:125]
	v_mfma_f32_16x16x32_bf16 v[94:97], v[110:113], v[210:213], v[94:97]
	v_mfma_f32_16x16x32_bf16 v[90:93], v[118:121], v[210:213], v[90:93]
	v_mfma_f32_16x16x32_bf16 v[82:85], v[110:113], v[228:231], v[82:85]
	v_mfma_f32_16x16x32_bf16 v[74:77], v[118:121], v[228:231], v[74:77]
	s_setprio 0
	s_setprio 1
	v_mfma_f32_16x16x32_bf16 v[134:137], v[162:165], v[178:181], v[134:137]
	v_mfma_f32_16x16x32_bf16 v[130:133], v[170:173], v[178:181], v[130:133]
	v_mfma_f32_16x16x32_bf16 v[106:109], v[162:165], v[186:189], v[106:109]
	v_mfma_f32_16x16x32_bf16 v[98:101], v[170:173], v[186:189], v[98:101]
	v_mfma_f32_16x16x32_bf16 v[86:89], v[162:165], v[206:209], v[86:89]
	v_mfma_f32_16x16x32_bf16 v[78:81], v[170:173], v[206:209], v[78:81]
	v_mfma_f32_16x16x32_bf16 v[70:73], v[162:165], v[214:217], v[70:73]
	v_mfma_f32_16x16x32_bf16 v[66:69], v[170:173], v[214:217], v[66:69]
	v_mfma_f32_16x16x32_bf16 v[134:137], v[166:169], v[182:185], v[134:137]
	v_mfma_f32_16x16x32_bf16 v[130:133], v[174:177], v[182:185], v[130:133]
	v_mfma_f32_16x16x32_bf16 v[106:109], v[166:169], v[202:205], v[106:109]
	v_mfma_f32_16x16x32_bf16 v[98:101], v[174:177], v[202:205], v[98:101]
	v_mfma_f32_16x16x32_bf16 v[86:89], v[166:169], v[210:213], v[86:89]
	v_mfma_f32_16x16x32_bf16 v[78:81], v[174:177], v[210:213], v[78:81]
	v_mfma_f32_16x16x32_bf16 v[70:73], v[166:169], v[228:231], v[70:73]
	v_mfma_f32_16x16x32_bf16 v[66:69], v[174:177], v[228:231], v[66:69]
	s_setprio 0
	s_barrier
	s_add_i32 s80, s80, s20
	v_lshl_add_u64 v[232:233], s[60:61], 0, v[150:151]
	s_mov_b32 m0, s80
	ds_read_b128 v[178:181], v161 offset:16384
	ds_read_b128 v[182:185], v161 offset:17408
	ds_read_b128 v[186:189], v161 offset:18432
	ds_read_b128 v[202:205], v161 offset:19456
	ds_read_b128 v[206:209], v161 offset:20480
	ds_read_b128 v[210:213], v161 offset:21504
	ds_read_b128 v[214:217], v161 offset:22528
	ds_read_b128 v[228:231], v161 offset:23552
	global_load_lds_dwordx4 v[232:233], off
	s_add_i32 m0, s80, 0x2000
	s_add_u32 s80, s60, 0x40000
	v_lshl_add_u64 v[234:235], s[60:61], 0, v[146:147]
	s_addc_u32 s81, s61, 0
	s_add_i32 s82, s82, s20
	global_load_lds_dwordx4 v[234:235], off
	v_lshl_add_u64 v[236:237], s[80:81], 0, v[150:151]
	s_mov_b32 m0, s82
	global_load_lds_dwordx4 v[236:237], off
	v_lshl_add_u64 v[236:237], s[80:81], 0, v[146:147]
	s_add_i32 m0, s82, 0x2000
	s_nop 0
	global_load_lds_dwordx4 v[236:237], off
	s_waitcnt vmcnt(6)
	s_waitcnt lgkmcnt(0)
	s_barrier
; #define PG8_STAGE(bufoff, gbase, voff) do { _Pragma("unroll") for (int _i = 0; _i < 2; ++_i) \
;         __builtin_amdgcn_global_load_lds((const unsigned*)((const char*)(gbase) + (voff)[_i]), (PG8_LAS unsigned*)(lds + (bufoff) + ldsw + _i * 8192), 16, 0, 0); } while (0)
; #define PG8_LDA(dst, b, h) do { _Pragma("unroll") for (int m = 0; m < 4; ++m) _Pragma("unroll") for (int k = 0; k < 2; ++k) dst[m][k] = *(const PG8_LAS bf16x8*)(lds + PG8_SA(b, h) + aoff + m * 2048 + k * 1024); } while (0)
; #define PG8_LDB(dst, b, h) do { _Pragma("unroll") for (int n = 0; n < 2; ++n) _Pragma("unroll") for (int k = 0; k < 2; ++k) dst[n][k] = *(const PG8_LAS bf16x8*)(lds + PG8_SB(b, h) + boff + n * 2048 + k * 1024); } while (0)
; #define PG8_MMA(ai, bj, At, Bt) do { __builtin_amdgcn_s_setprio(1); _Pragma("unroll") for (int m = 0; m < 4; ++m) _Pragma("unroll") for (int n = 0; n < 2; ++n) _Pragma("unroll") for (int k = 0; k < 2; ++k) \
;         acc[ai][bj][m][n] = __builtin_amdgcn_mfma_f32_16x16x32_bf16(Bt[n][k], At[m][k], acc[ai][bj][m][n], 0, 0, 0); __builtin_amdgcn_s_setprio(0); } while (0)
; #define PG8_WAIT_V(n) asm volatile("s_waitcnt vmcnt(" #n ")" ::: "memory")
; #define PG8_WAIT_L(n) asm volatile("s_waitcnt lgkmcnt(" #n ")" ::: "memory")
; #define PG8_BAR __builtin_amdgcn_s_barrier()
; #define PG8_SCHED __builtin_amdgcn_sched_barrier(0)
; template <class Epi, class Sched, bool ALIGN_EPI = false, bool SP2 = false>
; __device__ __forceinline__ void gemm_phase(PG8_LAS unsigned char* lds, const Gemm g, const Sched& S, const Epi& E) {
;     ...
;             PG8_WAIT_V(8); PG8_WAIT_L(0); PG8_BAR; PG8_MMA(1, 0, At, B0); PG8_MMA(1, 1, At, B1); PG8_BAR; PG8_SCHED;
;             PG8_LDB(B0, 1, 0); PG8_LDB(B1, 1, 1); PG8_SCHED; PG8_LDA(At, 1, 0); PG8_STAGE(PG8_SA(0, 1), a2 + hstep, voffA);
;             PG8_WAIT_V(8); PG8_WAIT_L(0); PG8_BAR; PG8_MMA(0, 0, At, B0); PG8_MMA(0, 1, At, B1); PG8_BAR; PG8_SCHED;
	s_setprio 1
	s_waitcnt lgkmcnt(0)
	v_mfma_f32_16x16x32_bf16 v[62:65], v[102:105], v[178:181], v[62:65]
	v_mfma_f32_16x16x32_bf16 v[58:61], v[114:117], v[178:181], v[58:61]
	v_mfma_f32_16x16x32_bf16 v[50:53], v[102:105], v[186:189], v[50:53]
	v_mfma_f32_16x16x32_bf16 v[42:45], v[114:117], v[186:189], v[42:45]
	v_mfma_f32_16x16x32_bf16 v[34:37], v[102:105], v[206:209], v[34:37]
	v_mfma_f32_16x16x32_bf16 v[26:29], v[114:117], v[206:209], v[26:29]
	v_mfma_f32_16x16x32_bf16 v[18:21], v[102:105], v[214:217], v[18:21]
	v_mfma_f32_16x16x32_bf16 v[10:13], v[114:117], v[214:217], v[10:13]
	v_mfma_f32_16x16x32_bf16 v[62:65], v[110:113], v[182:185], v[62:65]
	v_mfma_f32_16x16x32_bf16 v[58:61], v[118:121], v[182:185], v[58:61]
	v_mfma_f32_16x16x32_bf16 v[50:53], v[110:113], v[202:205], v[50:53]
	v_mfma_f32_16x16x32_bf16 v[42:45], v[118:121], v[202:205], v[42:45]
	v_mfma_f32_16x16x32_bf16 v[34:37], v[110:113], v[210:213], v[34:37]
	v_mfma_f32_16x16x32_bf16 v[26:29], v[118:121], v[210:213], v[26:29]
	v_mfma_f32_16x16x32_bf16 v[18:21], v[110:113], v[228:231], v[18:21]
	v_mfma_f32_16x16x32_bf16 v[10:13], v[118:121], v[228:231], v[10:13]
	s_setprio 0
	s_setprio 1
	v_mfma_f32_16x16x32_bf16 v[54:57], v[162:165], v[178:181], v[54:57]
	v_mfma_f32_16x16x32_bf16 v[46:49], v[170:173], v[178:181], v[46:49]
	v_mfma_f32_16x16x32_bf16 v[38:41], v[162:165], v[186:189], v[38:41]
	v_mfma_f32_16x16x32_bf16 v[30:33], v[170:173], v[186:189], v[30:33]
	v_mfma_f32_16x16x32_bf16 v[22:25], v[162:165], v[206:209], v[22:25]
	v_mfma_f32_16x16x32_bf16 v[14:17], v[170:173], v[206:209], v[14:17]
	v_mfma_f32_16x16x32_bf16 v[6:9], v[162:165], v[214:217], v[6:9]
	v_mfma_f32_16x16x32_bf16 v[2:5], v[170:173], v[214:217], v[2:5]
	v_mfma_f32_16x16x32_bf16 v[54:57], v[166:169], v[182:185], v[54:57]
	v_mfma_f32_16x16x32_bf16 v[46:49], v[174:177], v[182:185], v[46:49]
	v_mfma_f32_16x16x32_bf16 v[38:41], v[166:169], v[202:205], v[38:41]
	v_mfma_f32_16x16x32_bf16 v[30:33], v[174:177], v[202:205], v[30:33]
	v_mfma_f32_16x16x32_bf16 v[22:25], v[166:169], v[210:213], v[22:25]
	v_mfma_f32_16x16x32_bf16 v[14:17], v[174:177], v[210:213], v[14:17]
	v_mfma_f32_16x16x32_bf16 v[6:9], v[166:169], v[228:231], v[6:9]
	v_mfma_f32_16x16x32_bf16 v[2:5], v[174:177], v[228:231], v[2:5]
	s_setprio 0
	s_barrier
	v_lshl_add_u64 v[236:237], s[62:63], 0, v[152:153]
	s_mov_b32 m0, s28
	v_lshl_add_u64 v[238:239], s[62:63], 0, v[148:149]
	global_load_lds_dwordx4 v[236:237], off
	s_mov_b32 m0, s29
	s_nop 0
	global_load_lds_dwordx4 v[238:239], off
	s_add_i32 s80, 0, 0x18000
	v_add_u32_e32 v0, s80, v159
	s_add_i32 s81, 0, 0x1c000
	ds_read_b128 v[102:105], v0
	ds_read_b128 v[110:113], v0 offset:1024
	ds_read_b128 v[114:117], v0 offset:2048
	ds_read_b128 v[118:121], v0 offset:3072
	v_add_u32_e32 v0, s81, v159
	ds_read_b128 v[162:165], v0
	ds_read_b128 v[166:169], v0 offset:1024
	ds_read_b128 v[170:173], v0 offset:2048
	ds_read_b128 v[174:177], v0 offset:3072
	s_add_u32 s62, s62, 0x40000
	s_addc_u32 s63, s63, 0
	s_mov_b32 m0, s33
	v_lshl_add_u64 v[240:241], s[62:63], 0, v[152:153]
	ds_read_b128 v[178:181], v161 offset:32768
	ds_read_b128 v[182:185], v161 offset:33792
	ds_read_b128 v[186:189], v161 offset:34816
	ds_read_b128 v[202:205], v161 offset:35840
	ds_read_b128 v[206:209], v161 offset:36864
	ds_read_b128 v[210:213], v161 offset:37888
	ds_read_b128 v[214:217], v161 offset:38912
	ds_read_b128 v[228:231], v161 offset:39936
	global_load_lds_dwordx4 v[240:241], off
	v_lshl_add_u64 v[240:241], s[62:63], 0, v[148:149]
	s_mov_b32 m0, s64
	s_nop 0
	global_load_lds_dwordx4 v[240:241], off
	s_waitcnt vmcnt(8)
	s_waitcnt lgkmcnt(0)
	s_barrier
	s_setprio 1
	s_waitcnt lgkmcnt(0)
	v_mfma_f32_16x16x32_bf16 v[142:145], v[102:105], v[178:181], v[142:145]
	v_mfma_f32_16x16x32_bf16 v[138:141], v[114:117], v[178:181], v[138:141]
	v_mfma_f32_16x16x32_bf16 v[126:129], v[102:105], v[186:189], v[126:129]
	v_mfma_f32_16x16x32_bf16 v[122:125], v[114:117], v[186:189], v[122:125]
	v_mfma_f32_16x16x32_bf16 v[94:97], v[102:105], v[206:209], v[94:97]
	v_mfma_f32_16x16x32_bf16 v[90:93], v[114:117], v[206:209], v[90:93]
	v_mfma_f32_16x16x32_bf16 v[82:85], v[102:105], v[214:217], v[82:85]
	v_mfma_f32_16x16x32_bf16 v[74:77], v[114:117], v[214:217], v[74:77]
	v_mfma_f32_16x16x32_bf16 v[142:145], v[110:113], v[182:185], v[142:145]
	v_mfma_f32_16x16x32_bf16 v[138:141], v[118:121], v[182:185], v[138:141]
	v_mfma_f32_16x16x32_bf16 v[126:129], v[110:113], v[202:205], v[126:129]
	v_mfma_f32_16x16x32_bf16 v[122:125], v[118:121], v[202:205], v[122:125]
	v_mfma_f32_16x16x32_bf16 v[94:97], v[110:113], v[210:213], v[94:97]
	v_mfma_f32_16x16x32_bf16 v[90:93], v[118:121], v[210:213], v[90:93]
	v_mfma_f32_16x16x32_bf16 v[82:85], v[110:113], v[228:231], v[82:85]
	v_mfma_f32_16x16x32_bf16 v[74:77], v[118:121], v[228:231], v[74:77]
	s_setprio 0
	s_setprio 1
	v_mfma_f32_16x16x32_bf16 v[134:137], v[162:165], v[178:181], v[134:137]
	v_mfma_f32_16x16x32_bf16 v[130:133], v[170:173], v[178:181], v[130:133]
	v_mfma_f32_16x16x32_bf16 v[106:109], v[162:165], v[186:189], v[106:109]
	v_mfma_f32_16x16x32_bf16 v[98:101], v[170:173], v[186:189], v[98:101]
	v_mfma_f32_16x16x32_bf16 v[86:89], v[162:165], v[206:209], v[86:89]
	v_mfma_f32_16x16x32_bf16 v[78:81], v[170:173], v[206:209], v[78:81]
	v_mfma_f32_16x16x32_bf16 v[70:73], v[162:165], v[214:217], v[70:73]
	v_mfma_f32_16x16x32_bf16 v[66:69], v[170:173], v[214:217], v[66:69]
	v_mfma_f32_16x16x32_bf16 v[134:137], v[166:169], v[182:185], v[134:137]
	v_mfma_f32_16x16x32_bf16 v[130:133], v[174:177], v[182:185], v[130:133]
	v_mfma_f32_16x16x32_bf16 v[106:109], v[166:169], v[202:205], v[106:109]
	v_mfma_f32_16x16x32_bf16 v[98:101], v[174:177], v[202:205], v[98:101]
	v_mfma_f32_16x16x32_bf16 v[86:89], v[166:169], v[210:213], v[86:89]
	v_mfma_f32_16x16x32_bf16 v[78:81], v[174:177], v[210:213], v[78:81]
	v_mfma_f32_16x16x32_bf16 v[70:73], v[166:169], v[228:231], v[70:73]
	v_mfma_f32_16x16x32_bf16 v[66:69], v[174:177], v[228:231], v[66:69]
	s_setprio 0
	s_barrier
; #define PG8_STAGE(bufoff, gbase, voff) do { _Pragma("unroll") for (int _i = 0; _i < 2; ++_i) \
;         __builtin_amdgcn_global_load_lds((const unsigned*)((const char*)(gbase) + (voff)[_i]), (PG8_LAS unsigned*)(lds + (bufoff) + ldsw + _i * 8192), 16, 0, 0); } while (0)
; #define PG8_LDA(dst, b, h) do { _Pragma("unroll") for (int m = 0; m < 4; ++m) _Pragma("unroll") for (int k = 0; k < 2; ++k) dst[m][k] = *(const PG8_LAS bf16x8*)(lds + PG8_SA(b, h) + aoff + m * 2048 + k * 1024); } while (0)
; #define PG8_MMA(ai, bj, At, Bt) do { __builtin_amdgcn_s_setprio(1); _Pragma("unroll") for (int m = 0; m < 4; ++m) _Pragma("unroll") for (int n = 0; n < 2; ++n) _Pragma("unroll") for (int k = 0; k < 2; ++k) \
;         acc[ai][bj][m][n] = __builtin_amdgcn_mfma_f32_16x16x32_bf16(Bt[n][k], At[m][k], acc[ai][bj][m][n], 0, 0, 0); __builtin_amdgcn_s_setprio(0); } while (0)
; #define PG8_WAIT_V(n) asm volatile("s_waitcnt vmcnt(" #n ")" ::: "memory")
; #define PG8_WAIT_L(n) asm volatile("s_waitcnt lgkmcnt(" #n ")" ::: "memory")
; #define PG8_BAR __builtin_amdgcn_s_barrier()
; #define PG8_SCHED __builtin_amdgcn_sched_barrier(0)
; template <class Epi, class Sched, bool ALIGN_EPI = false, bool SP2 = false>
; __device__ __forceinline__ void gemm_phase(PG8_LAS unsigned char* lds, const Gemm g, const Sched& S, const Epi& E) {
;     ...
;         for (int t = 0; t < nt; t += 2) {
;     ...
;             PG8_WAIT_V(8); PG8_WAIT_L(0); PG8_BAR; PG8_MMA(0, 0, At, B0); PG8_MMA(0, 1, At, B1); PG8_BAR; PG8_SCHED;
;             PG8_LDA(At, 1, 1); PG8_STAGE(PG8_SB(1, 0), b3, voffB); PG8_STAGE(PG8_SB(1, 1), b3 + hstep, voffB); PG8_STAGE(PG8_SA(1, 0), a3, voffA);
;             PG8_WAIT_V(8); PG8_WAIT_L(0); PG8_BAR; PG8_MMA(1, 0, At, B0); PG8_MMA(1, 1, At, B1); PG8_BAR; PG8_SCHED;
	s_add_i32 s62, s80, s20
	v_lshl_add_u64 v[232:233], v[232:233], 0, s[38:39]
	s_mov_b32 m0, s62
	ds_read_b128 v[178:181], v161 offset:49152
	ds_read_b128 v[182:185], v161 offset:50176
	ds_read_b128 v[186:189], v161 offset:51200
	ds_read_b128 v[202:205], v161 offset:52224
	ds_read_b128 v[206:209], v161 offset:53248
	ds_read_b128 v[210:213], v161 offset:54272
	ds_read_b128 v[214:217], v161 offset:55296
	ds_read_b128 v[228:231], v161 offset:56320
	global_load_lds_dwordx4 v[232:233], off
	s_add_i32 m0, s62, 0x2000
	s_add_u32 s60, s60, 0x40080
	v_lshl_add_u64 v[232:233], v[234:235], 0, s[38:39]
	s_addc_u32 s61, s61, 0
	s_add_i32 s62, s81, s20
	global_load_lds_dwordx4 v[232:233], off
	v_lshl_add_u64 v[232:233], s[60:61], 0, v[150:151]
	s_mov_b32 m0, s62
	s_nop 0
	global_load_lds_dwordx4 v[232:233], off
	v_lshl_add_u64 v[232:233], s[60:61], 0, v[146:147]
	s_add_i32 m0, s62, 0x2000
	s_nop 0
	global_load_lds_dwordx4 v[232:233], off
	v_lshl_add_u64 v[232:233], v[236:237], 0, s[38:39]
	s_mov_b32 m0, s69
	s_nop 0
	global_load_lds_dwordx4 v[232:233], off
	v_lshl_add_u64 v[232:233], v[238:239], 0, s[38:39]
	s_mov_b32 m0, s70
	s_nop 0
	global_load_lds_dwordx4 v[232:233], off
	s_waitcnt vmcnt(8)
	s_waitcnt lgkmcnt(0)
	s_barrier
	s_setprio 1
	s_waitcnt lgkmcnt(0)
	v_mfma_f32_16x16x32_bf16 v[62:65], v[102:105], v[178:181], v[62:65]
	v_mfma_f32_16x16x32_bf16 v[58:61], v[114:117], v[178:181], v[58:61]
	v_mfma_f32_16x16x32_bf16 v[50:53], v[102:105], v[186:189], v[50:53]
	v_mfma_f32_16x16x32_bf16 v[42:45], v[114:117], v[186:189], v[42:45]
	v_mfma_f32_16x16x32_bf16 v[34:37], v[102:105], v[206:209], v[34:37]
	v_mfma_f32_16x16x32_bf16 v[26:29], v[114:117], v[206:209], v[26:29]
	v_mfma_f32_16x16x32_bf16 v[18:21], v[102:105], v[214:217], v[18:21]
	v_mfma_f32_16x16x32_bf16 v[10:13], v[114:117], v[214:217], v[10:13]
	v_mfma_f32_16x16x32_bf16 v[62:65], v[110:113], v[182:185], v[62:65]
	v_mfma_f32_16x16x32_bf16 v[58:61], v[118:121], v[182:185], v[58:61]
	v_mfma_f32_16x16x32_bf16 v[50:53], v[110:113], v[202:205], v[50:53]
	v_mfma_f32_16x16x32_bf16 v[42:45], v[118:121], v[202:205], v[42:45]
	v_mfma_f32_16x16x32_bf16 v[34:37], v[110:113], v[210:213], v[34:37]
	v_mfma_f32_16x16x32_bf16 v[26:29], v[118:121], v[210:213], v[26:29]
	v_mfma_f32_16x16x32_bf16 v[18:21], v[110:113], v[228:231], v[18:21]
	v_mfma_f32_16x16x32_bf16 v[10:13], v[118:121], v[228:231], v[10:13]
	s_setprio 0
	s_setprio 1
	v_mfma_f32_16x16x32_bf16 v[54:57], v[162:165], v[178:181], v[54:57]
	v_mfma_f32_16x16x32_bf16 v[46:49], v[170:173], v[178:181], v[46:49]
	v_mfma_f32_16x16x32_bf16 v[38:41], v[162:165], v[186:189], v[38:41]
	v_mfma_f32_16x16x32_bf16 v[30:33], v[170:173], v[186:189], v[30:33]
	v_mfma_f32_16x16x32_bf16 v[22:25], v[162:165], v[206:209], v[22:25]
	v_mfma_f32_16x16x32_bf16 v[14:17], v[170:173], v[206:209], v[14:17]
	v_mfma_f32_16x16x32_bf16 v[6:9], v[162:165], v[214:217], v[6:9]
	v_mfma_f32_16x16x32_bf16 v[2:5], v[170:173], v[214:217], v[2:5]
	v_mfma_f32_16x16x32_bf16 v[54:57], v[166:169], v[182:185], v[54:57]
	v_mfma_f32_16x16x32_bf16 v[46:49], v[174:177], v[182:185], v[46:49]
	v_mfma_f32_16x16x32_bf16 v[38:41], v[166:169], v[202:205], v[38:41]
	v_mfma_f32_16x16x32_bf16 v[30:33], v[174:177], v[202:205], v[30:33]
	v_mfma_f32_16x16x32_bf16 v[22:25], v[166:169], v[210:213], v[22:25]
	v_mfma_f32_16x16x32_bf16 v[14:17], v[174:177], v[210:213], v[14:17]
	v_mfma_f32_16x16x32_bf16 v[6:9], v[166:169], v[228:231], v[6:9]
	v_mfma_f32_16x16x32_bf16 v[2:5], v[174:177], v[228:231], v[2:5]
	s_setprio 0
	s_barrier
	s_add_i32 s79, s79, 2
	s_add_u32 s77, s77, 0x100
	s_addc_u32 s78, s78, 0
	s_add_u32 s42, s42, 0x100
	s_addc_u32 s43, s43, 0
	s_cmp_gt_u32 s79, 13
	s_cbranch_scc0 .LBB0_678
	s_and_b64 vcc, exec, s[44:45]
	s_movk_i32 s75, 0x1000
	s_cbranch_vccz .LBB0_681
	s_barrier
